# P8 hand epilogue with non-temporal loads of the residual base (read once there)
# baseline (speedup 1.0000x reference)
.LBB0_1028:
	ds_read_b128 v[128:131], v240
	ds_read_b128 v[132:135], v240 offset:1024
	ds_read_b128 v[136:139], v240 offset:2048
	ds_read_b128 v[140:143], v240 offset:3072
	ds_read_b128 v[144:147], v241
	ds_read_b128 v[148:151], v241 offset:1024
	ds_read_b128 v[152:155], v241 offset:2048
	ds_read_b128 v[156:159], v241 offset:3072
	s_add_u32 s24, s22, 0xfffc0080
	s_addc_u32 s25, s23, -1
	s_cmp_eq_u32 s50, 12
	s_cselect_b32 s27, s17, s25
	s_cselect_b32 s26, s46, s24
	s_cselect_b32 s25, s15, s49
	s_cselect_b32 s24, s47, s48
	v_lshl_add_u64 v[192:193], s[22:23], 0, v[218:219]
	s_add_i32 m0, s34, 0xc000
	ds_read_b128 v[160:163], v242
	ds_read_b128 v[164:167], v242 offset:1024
	ds_read_b128 v[168:171], v242 offset:2048
	ds_read_b128 v[172:175], v242 offset:3072
	ds_read_b128 v[176:179], v242 offset:4096
	ds_read_b128 v[180:183], v242 offset:5120
	ds_read_b128 v[184:187], v242 offset:6144
	ds_read_b128 v[188:191], v242 offset:7168
	global_load_lds_dwordx4 v[192:193], off
	v_lshl_add_u64 v[192:193], s[22:23], 0, v[220:221]
	s_add_i32 m0, s34, 0xe000
	s_nop 0
	global_load_lds_dwordx4 v[192:193], off
	s_waitcnt vmcnt(8)
	s_waitcnt lgkmcnt(0)
	s_barrier
	s_setprio 1
	s_waitcnt lgkmcnt(0)
	v_mfma_f32_16x16x32_bf16 v[124:127], v[128:131], v[160:163], v[124:127]
	v_mfma_f32_16x16x32_bf16 v[120:123], v[136:139], v[160:163], v[120:123]
	v_mfma_f32_16x16x32_bf16 v[112:115], v[128:131], v[168:171], v[112:115]
	v_mfma_f32_16x16x32_bf16 v[104:107], v[136:139], v[168:171], v[104:107]
	v_mfma_f32_16x16x32_bf16 v[96:99], v[128:131], v[176:179], v[96:99]
	v_mfma_f32_16x16x32_bf16 v[88:91], v[136:139], v[176:179], v[88:91]
	v_mfma_f32_16x16x32_bf16 v[76:79], v[128:131], v[184:187], v[76:79]
	v_mfma_f32_16x16x32_bf16 v[72:75], v[136:139], v[184:187], v[72:75]
	v_mfma_f32_16x16x32_bf16 v[124:127], v[132:135], v[164:167], v[124:127]
	v_mfma_f32_16x16x32_bf16 v[120:123], v[140:143], v[164:167], v[120:123]
	v_mfma_f32_16x16x32_bf16 v[112:115], v[132:135], v[172:175], v[112:115]
	v_mfma_f32_16x16x32_bf16 v[104:107], v[140:143], v[172:175], v[104:107]
	v_mfma_f32_16x16x32_bf16 v[96:99], v[132:135], v[180:183], v[96:99]
	v_mfma_f32_16x16x32_bf16 v[88:91], v[140:143], v[180:183], v[88:91]
	v_mfma_f32_16x16x32_bf16 v[76:79], v[132:135], v[188:191], v[76:79]
	v_mfma_f32_16x16x32_bf16 v[72:75], v[140:143], v[188:191], v[72:75]
	v_mfma_f32_16x16x32_bf16 v[116:119], v[144:147], v[160:163], v[116:119]
	v_mfma_f32_16x16x32_bf16 v[108:111], v[152:155], v[160:163], v[108:111]
	v_mfma_f32_16x16x32_bf16 v[100:103], v[144:147], v[168:171], v[100:103]
	v_mfma_f32_16x16x32_bf16 v[92:95], v[152:155], v[168:171], v[92:95]
	v_mfma_f32_16x16x32_bf16 v[84:87], v[144:147], v[176:179], v[84:87]
	v_mfma_f32_16x16x32_bf16 v[80:83], v[152:155], v[176:179], v[80:83]
	v_mfma_f32_16x16x32_bf16 v[68:71], v[144:147], v[184:187], v[68:71]
	v_mfma_f32_16x16x32_bf16 v[64:67], v[152:155], v[184:187], v[64:67]
	v_mfma_f32_16x16x32_bf16 v[116:119], v[148:151], v[164:167], v[116:119]
	v_mfma_f32_16x16x32_bf16 v[108:111], v[156:159], v[164:167], v[108:111]
	v_mfma_f32_16x16x32_bf16 v[100:103], v[148:151], v[172:175], v[100:103]
	v_mfma_f32_16x16x32_bf16 v[92:95], v[156:159], v[172:175], v[92:95]
	v_mfma_f32_16x16x32_bf16 v[84:87], v[148:151], v[180:183], v[84:87]
	v_mfma_f32_16x16x32_bf16 v[80:83], v[156:159], v[180:183], v[80:83]
	v_mfma_f32_16x16x32_bf16 v[68:71], v[148:151], v[188:191], v[68:71]
	v_mfma_f32_16x16x32_bf16 v[64:67], v[156:159], v[188:191], v[64:67]
	s_setprio 0
	s_barrier
	s_add_i32 s51, s44, s33
	v_lshl_add_u64 v[192:193], s[24:25], 0, v[212:213]
	s_mov_b32 m0, s51
	ds_read_b128 v[160:163], v242 offset:16384
	ds_read_b128 v[164:167], v242 offset:17408
	ds_read_b128 v[168:171], v242 offset:18432
	ds_read_b128 v[172:175], v242 offset:19456
	ds_read_b128 v[176:179], v242 offset:20480
	ds_read_b128 v[180:183], v242 offset:21504
	ds_read_b128 v[184:187], v242 offset:22528
	ds_read_b128 v[188:191], v242 offset:23552
	global_load_lds_dwordx4 v[192:193], off
	s_add_i32 m0, s51, 0x2000
	s_add_u32 s52, s24, 0x40000
	v_lshl_add_u64 v[194:195], s[24:25], 0, v[216:217]
	s_addc_u32 s53, s25, 0
	s_add_i32 s51, s45, s33
	global_load_lds_dwordx4 v[194:195], off
	v_lshl_add_u64 v[196:197], s[52:53], 0, v[212:213]
	s_mov_b32 m0, s51
	v_lshl_add_u64 v[198:199], s[26:27], 0, v[214:215]
	global_load_lds_dwordx4 v[196:197], off
	v_lshl_add_u64 v[196:197], s[52:53], 0, v[216:217]
	s_add_i32 m0, s51, 0x2000
	s_nop 0
	global_load_lds_dwordx4 v[196:197], off
	v_lshl_add_u64 v[196:197], s[26:27], 0, v[210:211]
	s_mov_b32 m0, s34
	s_nop 0
	global_load_lds_dwordx4 v[196:197], off
	s_mov_b32 m0, s35
	s_nop 0
	global_load_lds_dwordx4 v[198:199], off
	s_waitcnt vmcnt(8)
	s_waitcnt lgkmcnt(0)
	s_barrier
	s_setprio 1
	s_waitcnt lgkmcnt(0)
	v_mfma_f32_16x16x32_bf16 v[60:63], v[128:131], v[160:163], v[60:63]
	v_mfma_f32_16x16x32_bf16 v[56:59], v[136:139], v[160:163], v[56:59]
	v_mfma_f32_16x16x32_bf16 v[48:51], v[128:131], v[168:171], v[48:51]
	v_mfma_f32_16x16x32_bf16 v[40:43], v[136:139], v[168:171], v[40:43]
	v_mfma_f32_16x16x32_bf16 v[32:35], v[128:131], v[176:179], v[32:35]
	v_mfma_f32_16x16x32_bf16 v[24:27], v[136:139], v[176:179], v[24:27]
	v_mfma_f32_16x16x32_bf16 v[12:15], v[128:131], v[184:187], v[12:15]
	v_mfma_f32_16x16x32_bf16 v[8:11], v[136:139], v[184:187], v[8:11]
	v_mfma_f32_16x16x32_bf16 v[60:63], v[132:135], v[164:167], v[60:63]
	v_mfma_f32_16x16x32_bf16 v[56:59], v[140:143], v[164:167], v[56:59]
	v_mfma_f32_16x16x32_bf16 v[48:51], v[132:135], v[172:175], v[48:51]
	v_mfma_f32_16x16x32_bf16 v[40:43], v[140:143], v[172:175], v[40:43]
	v_mfma_f32_16x16x32_bf16 v[32:35], v[132:135], v[180:183], v[32:35]
	v_mfma_f32_16x16x32_bf16 v[24:27], v[140:143], v[180:183], v[24:27]
	v_mfma_f32_16x16x32_bf16 v[12:15], v[132:135], v[188:191], v[12:15]
	v_mfma_f32_16x16x32_bf16 v[8:11], v[140:143], v[188:191], v[8:11]
	v_mfma_f32_16x16x32_bf16 v[52:55], v[144:147], v[160:163], v[52:55]
	v_mfma_f32_16x16x32_bf16 v[44:47], v[152:155], v[160:163], v[44:47]
	v_mfma_f32_16x16x32_bf16 v[36:39], v[144:147], v[168:171], v[36:39]
	v_mfma_f32_16x16x32_bf16 v[28:31], v[152:155], v[168:171], v[28:31]
	v_mfma_f32_16x16x32_bf16 v[20:23], v[144:147], v[176:179], v[20:23]
	v_mfma_f32_16x16x32_bf16 v[16:19], v[152:155], v[176:179], v[16:19]
	v_mfma_f32_16x16x32_bf16 v[4:7], v[144:147], v[184:187], v[4:7]
	v_mfma_f32_16x16x32_bf16 v[0:3], v[152:155], v[184:187], v[0:3]
	v_mfma_f32_16x16x32_bf16 v[52:55], v[148:151], v[164:167], v[52:55]
	v_mfma_f32_16x16x32_bf16 v[44:47], v[156:159], v[164:167], v[44:47]
	v_mfma_f32_16x16x32_bf16 v[36:39], v[148:151], v[172:175], v[36:39]
	v_mfma_f32_16x16x32_bf16 v[28:31], v[156:159], v[172:175], v[28:31]
	v_mfma_f32_16x16x32_bf16 v[20:23], v[148:151], v[180:183], v[20:23]
	v_mfma_f32_16x16x32_bf16 v[16:19], v[156:159], v[180:183], v[16:19]
	v_mfma_f32_16x16x32_bf16 v[4:7], v[148:151], v[188:191], v[4:7]
	v_mfma_f32_16x16x32_bf16 v[0:3], v[156:159], v[188:191], v[0:3]
	s_setprio 0
	s_barrier
	s_add_i32 s51, 0, 0x18000
	s_add_i32 s52, 0, 0x1c000
	v_add_u32_e32 v140, s51, v238
	v_add_u32_e32 v156, s52, v238
	ds_read_b128 v[128:131], v140
	ds_read_b128 v[132:135], v140 offset:1024
	ds_read_b128 v[136:139], v140 offset:2048
	ds_read_b128 v[140:143], v140 offset:3072
	ds_read_b128 v[144:147], v156
	ds_read_b128 v[148:151], v156 offset:1024
	ds_read_b128 v[152:155], v156 offset:2048
	ds_read_b128 v[156:159], v156 offset:3072
	s_add_u32 s26, s26, 0x40000
	s_addc_u32 s27, s27, 0
	s_mov_b32 m0, s36
	v_lshl_add_u64 v[200:201], s[26:27], 0, v[210:211]
	ds_read_b128 v[160:163], v242 offset:32768
	ds_read_b128 v[164:167], v242 offset:33792
	ds_read_b128 v[168:171], v242 offset:34816
	ds_read_b128 v[172:175], v242 offset:35840
	ds_read_b128 v[176:179], v242 offset:36864
	ds_read_b128 v[180:183], v242 offset:37888
	ds_read_b128 v[184:187], v242 offset:38912
	ds_read_b128 v[188:191], v242 offset:39936
	global_load_lds_dwordx4 v[200:201], off
	v_lshl_add_u64 v[200:201], s[26:27], 0, v[214:215]
	s_mov_b32 m0, s37
	s_nop 0
	global_load_lds_dwordx4 v[200:201], off
	s_waitcnt vmcnt(8)
	s_waitcnt lgkmcnt(0)
	s_barrier
	s_setprio 1
	s_waitcnt lgkmcnt(0)
	v_mfma_f32_16x16x32_bf16 v[124:127], v[128:131], v[160:163], v[124:127]
	v_mfma_f32_16x16x32_bf16 v[120:123], v[136:139], v[160:163], v[120:123]
	v_mfma_f32_16x16x32_bf16 v[112:115], v[128:131], v[168:171], v[112:115]
	v_mfma_f32_16x16x32_bf16 v[104:107], v[136:139], v[168:171], v[104:107]
	v_mfma_f32_16x16x32_bf16 v[96:99], v[128:131], v[176:179], v[96:99]
	v_mfma_f32_16x16x32_bf16 v[88:91], v[136:139], v[176:179], v[88:91]
	v_mfma_f32_16x16x32_bf16 v[76:79], v[128:131], v[184:187], v[76:79]
	v_mfma_f32_16x16x32_bf16 v[72:75], v[136:139], v[184:187], v[72:75]
	v_mfma_f32_16x16x32_bf16 v[124:127], v[132:135], v[164:167], v[124:127]
	v_mfma_f32_16x16x32_bf16 v[120:123], v[140:143], v[164:167], v[120:123]
	v_mfma_f32_16x16x32_bf16 v[112:115], v[132:135], v[172:175], v[112:115]
	v_mfma_f32_16x16x32_bf16 v[104:107], v[140:143], v[172:175], v[104:107]
	v_mfma_f32_16x16x32_bf16 v[96:99], v[132:135], v[180:183], v[96:99]
	v_mfma_f32_16x16x32_bf16 v[88:91], v[140:143], v[180:183], v[88:91]
	v_mfma_f32_16x16x32_bf16 v[76:79], v[132:135], v[188:191], v[76:79]
	v_mfma_f32_16x16x32_bf16 v[72:75], v[140:143], v[188:191], v[72:75]
	v_mfma_f32_16x16x32_bf16 v[116:119], v[144:147], v[160:163], v[116:119]
	v_mfma_f32_16x16x32_bf16 v[108:111], v[152:155], v[160:163], v[108:111]
	v_mfma_f32_16x16x32_bf16 v[100:103], v[144:147], v[168:171], v[100:103]
	v_mfma_f32_16x16x32_bf16 v[92:95], v[152:155], v[168:171], v[92:95]
	v_mfma_f32_16x16x32_bf16 v[84:87], v[144:147], v[176:179], v[84:87]
	v_mfma_f32_16x16x32_bf16 v[80:83], v[152:155], v[176:179], v[80:83]
	v_mfma_f32_16x16x32_bf16 v[68:71], v[144:147], v[184:187], v[68:71]
	v_mfma_f32_16x16x32_bf16 v[64:67], v[152:155], v[184:187], v[64:67]
	v_mfma_f32_16x16x32_bf16 v[116:119], v[148:151], v[164:167], v[116:119]
	v_mfma_f32_16x16x32_bf16 v[108:111], v[156:159], v[164:167], v[108:111]
	v_mfma_f32_16x16x32_bf16 v[100:103], v[148:151], v[172:175], v[100:103]
	v_mfma_f32_16x16x32_bf16 v[92:95], v[156:159], v[172:175], v[92:95]
	v_mfma_f32_16x16x32_bf16 v[84:87], v[148:151], v[180:183], v[84:87]
	v_mfma_f32_16x16x32_bf16 v[80:83], v[156:159], v[180:183], v[80:83]
	v_mfma_f32_16x16x32_bf16 v[68:71], v[148:151], v[188:191], v[68:71]
	v_mfma_f32_16x16x32_bf16 v[64:67], v[156:159], v[188:191], v[64:67]
	s_setprio 0
	s_barrier
	s_add_i32 s26, s51, s33
	v_lshl_add_u64 v[192:193], v[192:193], 0, s[12:13]
	s_mov_b32 m0, s26
	ds_read_b128 v[160:163], v242 offset:49152
	ds_read_b128 v[164:167], v242 offset:50176
	ds_read_b128 v[168:171], v242 offset:51200
	ds_read_b128 v[172:175], v242 offset:52224
	ds_read_b128 v[176:179], v242 offset:53248
	ds_read_b128 v[180:183], v242 offset:54272
	ds_read_b128 v[184:187], v242 offset:55296
	ds_read_b128 v[188:191], v242 offset:56320
	global_load_lds_dwordx4 v[192:193], off
	s_add_i32 m0, s26, 0x2000
	s_add_u32 s24, s24, 0x40080
	v_lshl_add_u64 v[192:193], v[194:195], 0, s[12:13]
	s_addc_u32 s25, s25, 0
	s_add_i32 s26, s52, s33
	global_load_lds_dwordx4 v[192:193], off
	v_lshl_add_u64 v[192:193], s[24:25], 0, v[212:213]
	s_mov_b32 m0, s26
	s_nop 0
	global_load_lds_dwordx4 v[192:193], off
	v_lshl_add_u64 v[192:193], s[24:25], 0, v[216:217]
	s_add_i32 m0, s26, 0x2000
	s_nop 0
	global_load_lds_dwordx4 v[192:193], off
	v_lshl_add_u64 v[192:193], v[196:197], 0, s[12:13]
	s_mov_b32 m0, s39
	s_nop 0
	global_load_lds_dwordx4 v[192:193], off
	v_lshl_add_u64 v[192:193], v[198:199], 0, s[12:13]
	s_mov_b32 m0, s40
	s_nop 0
	global_load_lds_dwordx4 v[192:193], off
	s_waitcnt vmcnt(8)
	s_waitcnt lgkmcnt(0)
	s_barrier
	s_setprio 1
	s_waitcnt lgkmcnt(0)
	v_mfma_f32_16x16x32_bf16 v[60:63], v[128:131], v[160:163], v[60:63]
	v_mfma_f32_16x16x32_bf16 v[56:59], v[136:139], v[160:163], v[56:59]
	v_mfma_f32_16x16x32_bf16 v[48:51], v[128:131], v[168:171], v[48:51]
	v_mfma_f32_16x16x32_bf16 v[40:43], v[136:139], v[168:171], v[40:43]
	v_mfma_f32_16x16x32_bf16 v[32:35], v[128:131], v[176:179], v[32:35]
	v_mfma_f32_16x16x32_bf16 v[24:27], v[136:139], v[176:179], v[24:27]
	v_mfma_f32_16x16x32_bf16 v[12:15], v[128:131], v[184:187], v[12:15]
	v_mfma_f32_16x16x32_bf16 v[8:11], v[136:139], v[184:187], v[8:11]
	v_mfma_f32_16x16x32_bf16 v[60:63], v[132:135], v[164:167], v[60:63]
	v_mfma_f32_16x16x32_bf16 v[56:59], v[140:143], v[164:167], v[56:59]
	v_mfma_f32_16x16x32_bf16 v[48:51], v[132:135], v[172:175], v[48:51]
	v_mfma_f32_16x16x32_bf16 v[40:43], v[140:143], v[172:175], v[40:43]
	v_mfma_f32_16x16x32_bf16 v[32:35], v[132:135], v[180:183], v[32:35]
	v_mfma_f32_16x16x32_bf16 v[24:27], v[140:143], v[180:183], v[24:27]
	v_mfma_f32_16x16x32_bf16 v[12:15], v[132:135], v[188:191], v[12:15]
	v_mfma_f32_16x16x32_bf16 v[8:11], v[140:143], v[188:191], v[8:11]
	v_mfma_f32_16x16x32_bf16 v[52:55], v[144:147], v[160:163], v[52:55]
	v_mfma_f32_16x16x32_bf16 v[44:47], v[152:155], v[160:163], v[44:47]
	v_mfma_f32_16x16x32_bf16 v[36:39], v[144:147], v[168:171], v[36:39]
	v_mfma_f32_16x16x32_bf16 v[28:31], v[152:155], v[168:171], v[28:31]
	v_mfma_f32_16x16x32_bf16 v[20:23], v[144:147], v[176:179], v[20:23]
	v_mfma_f32_16x16x32_bf16 v[16:19], v[152:155], v[176:179], v[16:19]
	v_mfma_f32_16x16x32_bf16 v[4:7], v[144:147], v[184:187], v[4:7]
	v_mfma_f32_16x16x32_bf16 v[0:3], v[152:155], v[184:187], v[0:3]
	v_mfma_f32_16x16x32_bf16 v[52:55], v[148:151], v[164:167], v[52:55]
	v_mfma_f32_16x16x32_bf16 v[44:47], v[156:159], v[164:167], v[44:47]
	v_mfma_f32_16x16x32_bf16 v[36:39], v[148:151], v[172:175], v[36:39]
	v_mfma_f32_16x16x32_bf16 v[28:31], v[156:159], v[172:175], v[28:31]
	v_mfma_f32_16x16x32_bf16 v[20:23], v[148:151], v[180:183], v[20:23]
	v_mfma_f32_16x16x32_bf16 v[16:19], v[156:159], v[180:183], v[16:19]
	v_mfma_f32_16x16x32_bf16 v[4:7], v[148:151], v[188:191], v[4:7]
	v_mfma_f32_16x16x32_bf16 v[0:3], v[156:159], v[188:191], v[0:3]
	s_setprio 0
	s_barrier
	s_add_i32 s50, s50, 2
	s_add_u32 s22, s22, 0x100
	s_addc_u32 s23, s23, 0
	s_add_u32 s48, s48, 0x100
	s_addc_u32 s49, s49, 0
	s_cmp_gt_u32 s50, 13
	s_cbranch_scc0 .LBB0_1028
	s_cmpk_lg_i32 s78, 0x100
	s_cbranch_scc1 .Lepi8_orig
	s_nop 7
	s_nop 7
	v_and_b32_e32 v228, 15, v236
	v_lshrrev_b32_e32 v229, 8, v236
	v_lshl_add_u32 v228, v229, 6, v228
	v_lshlrev_b32_e32 v228, 12, v228
	v_bfe_u32 v229, v236, 6, 2
	v_bfe_u32 v230, v236, 4, 2
	v_lshlrev_b32_e32 v229, 7, v229
	v_lshl_or_b32 v229, v230, 5, v229
	v_add_u32_e32 v228, v228, v229
	s_lshr_b32 vcc_lo, s4, 3
	s_mul_i32 vcc_lo, vcc_lo, 0x9000
	s_lshl_b32 vcc_hi, s5, 10
	s_add_i32 vcc_lo, vcc_lo, vcc_hi
	s_add_u32 s98, s74, 0x5000
	s_addc_u32 s99, s75, 0
	s_add_u32 s98, s98, vcc_lo
	s_addc_u32 s99, s99, 0
	global_load_dwordx4 v[210:213], v229, s[98:99]
	global_load_dwordx4 v[214:217], v229, s[98:99] offset:16
	global_load_dwordx4 v[218:221], v229, s[98:99] offset:512
	global_load_dwordx4 v[222:225], v229, s[98:99] offset:528
	s_lshl_b32 vcc_lo, s4, 20
	s_add_i32 vcc_lo, vcc_lo, vcc_hi
	s_add_u32 s98, s72, vcc_lo
	s_addc_u32 s99, s73, 0
	s_add_u32 s100, s72, vcc_lo
	s_addc_u32 s101, s73, 0
	global_load_dwordx4 v[128:131], v228, s[98:99] nt
	global_load_dwordx4 v[132:135], v228, s[98:99] offset:16 nt
	global_load_dwordx4 v[136:139], v228, s[98:99] offset:512 nt
	global_load_dwordx4 v[140:143], v228, s[98:99] offset:528 nt
	s_add_u32 s98, s98, 0x10000
	s_addc_u32 s99, s99, 0
	global_load_dwordx4 v[144:147], v228, s[98:99] nt
	global_load_dwordx4 v[148:151], v228, s[98:99] offset:16 nt
	global_load_dwordx4 v[152:155], v228, s[98:99] offset:512 nt
	global_load_dwordx4 v[156:159], v228, s[98:99] offset:528 nt
	s_add_u32 s98, s98, 0x10000
	s_addc_u32 s99, s99, 0
	global_load_dwordx4 v[160:163], v228, s[98:99] nt
	global_load_dwordx4 v[164:167], v228, s[98:99] offset:16 nt
	global_load_dwordx4 v[168:171], v228, s[98:99] offset:512 nt
	global_load_dwordx4 v[172:175], v228, s[98:99] offset:528 nt
	s_add_u32 s98, s98, 0x10000
	s_addc_u32 s99, s99, 0
	global_load_dwordx4 v[176:179], v228, s[98:99] nt
	global_load_dwordx4 v[180:183], v228, s[98:99] offset:16 nt
	global_load_dwordx4 v[184:187], v228, s[98:99] offset:512 nt
	global_load_dwordx4 v[188:191], v228, s[98:99] offset:528 nt
	s_add_u32 s98, s98, 0x50000
	s_addc_u32 s99, s99, 0
	global_load_dwordx4 v[192:195], v228, s[98:99] nt
	global_load_dwordx4 v[196:199], v228, s[98:99] offset:16 nt
	global_load_dwordx4 v[200:203], v228, s[98:99] offset:512 nt
	global_load_dwordx4 v[204:207], v228, s[98:99] offset:528 nt
	s_add_u32 s98, s98, 0x10000
	s_addc_u32 s99, s99, 0
	s_waitcnt vmcnt(16)
	v_pk_fma_f32 v[124:125], v[124:125], v[210:211], v[128:129]
	v_pk_fma_f32 v[126:127], v[126:127], v[212:213], v[130:131]
	v_pk_fma_f32 v[120:121], v[120:121], v[214:215], v[132:133]
	v_pk_fma_f32 v[122:123], v[122:123], v[216:217], v[134:135]
	v_pk_fma_f32 v[116:117], v[116:117], v[218:219], v[136:137]
	v_pk_fma_f32 v[118:119], v[118:119], v[220:221], v[138:139]
	v_pk_fma_f32 v[108:109], v[108:109], v[222:223], v[140:141]
	v_pk_fma_f32 v[110:111], v[110:111], v[224:225], v[142:143]
	global_store_dwordx4 v228, v[124:127], s[100:101]
	global_store_dwordx4 v228, v[120:123], s[100:101] offset:16
	global_store_dwordx4 v228, v[116:119], s[100:101] offset:512
	global_store_dwordx4 v228, v[108:111], s[100:101] offset:528
	s_add_u32 s100, s100, 0x10000
	s_addc_u32 s101, s101, 0
	global_load_dwordx4 v[128:131], v228, s[98:99] nt
	global_load_dwordx4 v[132:135], v228, s[98:99] offset:16 nt
	global_load_dwordx4 v[136:139], v228, s[98:99] offset:512 nt
	global_load_dwordx4 v[140:143], v228, s[98:99] offset:528 nt
	s_add_u32 s98, s98, 0x10000
	s_addc_u32 s99, s99, 0
	s_waitcnt vmcnt(20)
	v_pk_fma_f32 v[112:113], v[112:113], v[210:211], v[144:145]
	v_pk_fma_f32 v[114:115], v[114:115], v[212:213], v[146:147]
	v_pk_fma_f32 v[104:105], v[104:105], v[214:215], v[148:149]
	v_pk_fma_f32 v[106:107], v[106:107], v[216:217], v[150:151]
	v_pk_fma_f32 v[100:101], v[100:101], v[218:219], v[152:153]
	v_pk_fma_f32 v[102:103], v[102:103], v[220:221], v[154:155]
	v_pk_fma_f32 v[92:93], v[92:93], v[222:223], v[156:157]
	v_pk_fma_f32 v[94:95], v[94:95], v[224:225], v[158:159]
	global_store_dwordx4 v228, v[112:115], s[100:101]
	global_store_dwordx4 v228, v[104:107], s[100:101] offset:16
	global_store_dwordx4 v228, v[100:103], s[100:101] offset:512
	global_store_dwordx4 v228, v[92:95], s[100:101] offset:528
	s_add_u32 s100, s100, 0x10000
	s_addc_u32 s101, s101, 0
	global_load_dwordx4 v[144:147], v228, s[98:99] nt
	global_load_dwordx4 v[148:151], v228, s[98:99] offset:16 nt
	global_load_dwordx4 v[152:155], v228, s[98:99] offset:512 nt
	global_load_dwordx4 v[156:159], v228, s[98:99] offset:528 nt
	s_add_u32 s98, s98, 0x10000
	s_addc_u32 s99, s99, 0
	s_waitcnt vmcnt(24)
	v_pk_fma_f32 v[96:97], v[96:97], v[210:211], v[160:161]
	v_pk_fma_f32 v[98:99], v[98:99], v[212:213], v[162:163]
	v_pk_fma_f32 v[88:89], v[88:89], v[214:215], v[164:165]
	v_pk_fma_f32 v[90:91], v[90:91], v[216:217], v[166:167]
	v_pk_fma_f32 v[84:85], v[84:85], v[218:219], v[168:169]
	v_pk_fma_f32 v[86:87], v[86:87], v[220:221], v[170:171]
	v_pk_fma_f32 v[80:81], v[80:81], v[222:223], v[172:173]
	v_pk_fma_f32 v[82:83], v[82:83], v[224:225], v[174:175]
	global_store_dwordx4 v228, v[96:99], s[100:101]
	global_store_dwordx4 v228, v[88:91], s[100:101] offset:16
	global_store_dwordx4 v228, v[84:87], s[100:101] offset:512
	global_store_dwordx4 v228, v[80:83], s[100:101] offset:528
	s_add_u32 s100, s100, 0x10000
	s_addc_u32 s101, s101, 0
	global_load_dwordx4 v[160:163], v228, s[98:99] nt
	global_load_dwordx4 v[164:167], v228, s[98:99] offset:16 nt
	global_load_dwordx4 v[168:171], v228, s[98:99] offset:512 nt
	global_load_dwordx4 v[172:175], v228, s[98:99] offset:528 nt
	s_waitcnt vmcnt(28)
	v_pk_fma_f32 v[76:77], v[76:77], v[210:211], v[176:177]
	v_pk_fma_f32 v[78:79], v[78:79], v[212:213], v[178:179]
	v_pk_fma_f32 v[72:73], v[72:73], v[214:215], v[180:181]
	v_pk_fma_f32 v[74:75], v[74:75], v[216:217], v[182:183]
	v_pk_fma_f32 v[68:69], v[68:69], v[218:219], v[184:185]
	v_pk_fma_f32 v[70:71], v[70:71], v[220:221], v[186:187]
	v_pk_fma_f32 v[64:65], v[64:65], v[222:223], v[188:189]
	v_pk_fma_f32 v[66:67], v[66:67], v[224:225], v[190:191]
	global_store_dwordx4 v228, v[76:79], s[100:101]
	global_store_dwordx4 v228, v[72:75], s[100:101] offset:16
	global_store_dwordx4 v228, v[68:71], s[100:101] offset:512
	global_store_dwordx4 v228, v[64:67], s[100:101] offset:528
	s_add_u32 s100, s100, 0x50000
	s_addc_u32 s101, s101, 0
	s_waitcnt vmcnt(28)
	v_pk_fma_f32 v[60:61], v[60:61], v[210:211], v[192:193]
	v_pk_fma_f32 v[62:63], v[62:63], v[212:213], v[194:195]
	v_pk_fma_f32 v[56:57], v[56:57], v[214:215], v[196:197]
	v_pk_fma_f32 v[58:59], v[58:59], v[216:217], v[198:199]
	v_pk_fma_f32 v[52:53], v[52:53], v[218:219], v[200:201]
	v_pk_fma_f32 v[54:55], v[54:55], v[220:221], v[202:203]
	v_pk_fma_f32 v[44:45], v[44:45], v[222:223], v[204:205]
	v_pk_fma_f32 v[46:47], v[46:47], v[224:225], v[206:207]
	global_store_dwordx4 v228, v[60:63], s[100:101]
	global_store_dwordx4 v228, v[56:59], s[100:101] offset:16
	global_store_dwordx4 v228, v[52:55], s[100:101] offset:512
	global_store_dwordx4 v228, v[44:47], s[100:101] offset:528
	s_add_u32 s100, s100, 0x10000
	s_addc_u32 s101, s101, 0
	s_waitcnt vmcnt(24)
	v_pk_fma_f32 v[48:49], v[48:49], v[210:211], v[128:129]
	v_pk_fma_f32 v[50:51], v[50:51], v[212:213], v[130:131]
	v_pk_fma_f32 v[40:41], v[40:41], v[214:215], v[132:133]
	v_pk_fma_f32 v[42:43], v[42:43], v[216:217], v[134:135]
	v_pk_fma_f32 v[36:37], v[36:37], v[218:219], v[136:137]
	v_pk_fma_f32 v[38:39], v[38:39], v[220:221], v[138:139]
	v_pk_fma_f32 v[28:29], v[28:29], v[222:223], v[140:141]
	v_pk_fma_f32 v[30:31], v[30:31], v[224:225], v[142:143]
	global_store_dwordx4 v228, v[48:51], s[100:101]
	global_store_dwordx4 v228, v[40:43], s[100:101] offset:16
	global_store_dwordx4 v228, v[36:39], s[100:101] offset:512
	global_store_dwordx4 v228, v[28:31], s[100:101] offset:528
	s_add_u32 s100, s100, 0x10000
	s_addc_u32 s101, s101, 0
	s_waitcnt vmcnt(20)
	v_pk_fma_f32 v[32:33], v[32:33], v[210:211], v[144:145]
	v_pk_fma_f32 v[34:35], v[34:35], v[212:213], v[146:147]
	v_pk_fma_f32 v[24:25], v[24:25], v[214:215], v[148:149]
	v_pk_fma_f32 v[26:27], v[26:27], v[216:217], v[150:151]
	v_pk_fma_f32 v[20:21], v[20:21], v[218:219], v[152:153]
	v_pk_fma_f32 v[22:23], v[22:23], v[220:221], v[154:155]
	v_pk_fma_f32 v[16:17], v[16:17], v[222:223], v[156:157]
	v_pk_fma_f32 v[18:19], v[18:19], v[224:225], v[158:159]
	global_store_dwordx4 v228, v[32:35], s[100:101]
	global_store_dwordx4 v228, v[24:27], s[100:101] offset:16
	global_store_dwordx4 v228, v[20:23], s[100:101] offset:512
	global_store_dwordx4 v228, v[16:19], s[100:101] offset:528
	s_add_u32 s100, s100, 0x10000
	s_addc_u32 s101, s101, 0
	s_waitcnt vmcnt(16)
	v_pk_fma_f32 v[12:13], v[12:13], v[210:211], v[160:161]
	v_pk_fma_f32 v[14:15], v[14:15], v[212:213], v[162:163]
	v_pk_fma_f32 v[8:9], v[8:9], v[214:215], v[164:165]
	v_pk_fma_f32 v[10:11], v[10:11], v[216:217], v[166:167]
	v_pk_fma_f32 v[4:5], v[4:5], v[218:219], v[168:169]
	v_pk_fma_f32 v[6:7], v[6:7], v[220:221], v[170:171]
	v_pk_fma_f32 v[0:1], v[0:1], v[222:223], v[172:173]
	v_pk_fma_f32 v[2:3], v[2:3], v[224:225], v[174:175]
	global_store_dwordx4 v228, v[12:15], s[100:101]
	global_store_dwordx4 v228, v[8:11], s[100:101] offset:16
	global_store_dwordx4 v228, v[4:7], s[100:101] offset:512
	global_store_dwordx4 v228, v[0:3], s[100:101] offset:528
	s_branch .LBB0_1037
